# v25 + relu quieting fusion in the up-GEMM epilogue + conditional vmcnt(24) waits after unit epilogues (P1, P7)
# baseline (speedup 1.0000x reference)
; __device__ __forceinline__ unsigned cvt_pk_bf16(float lo, float hi) { unsigned r; asm volatile("v_cvt_pk_bf16_f32 %0, %1, %2" : "=v"(r) : "v"(lo), "v"(hi)); return r; }
;     __device__ __forceinline__ void operator()(const f32x4 (&acc)[2][2][4][2], const Unit& u, int wr, int wc, int fr, int fq) const {
;         const int row0 = u.pm * BM + wr * 64 + fr, col0 = u.pn * BM + wc * CWS + 8 * fq;
;         float rs[2][4];
;         if (ROWSCALE) {
; #pragma unroll
;             for (int ai = 0; ai < 2; ++ai)
; #pragma unroll
;                 for (int m = 0; m < 4; ++m) { const f32x4 q = *(const f32x4*)(ssq4 + (size_t)(row0 + ai * HALF + m * 16) * 4); rs[ai][m] = 1.0f / sqrtf(((q[0] + q[1]) + (q[2] + q[3])) * (1.0f / 1024.0f) + eps); }
;         }
; #pragma unroll
;         for (int ai = 0; ai < 2; ++ai)
; #pragma unroll
;             for (int m = 0; m < 4; ++m) { bf16_t* rowp = O + (size_t)(row0 + ai * HALF + m * 16) * ldc + col0;
; #pragma unroll
;                 for (int bj = 0; bj < 2; ++bj) { f32x4 v0 = acc[ai][bj][m][0], v1 = acc[ai][bj][m][1];
;                     if (ROWSCALE) { v0 = v0 * rs[ai][m]; v1 = v1 * rs[ai][m]; }
;                     if (ACT == 2) {
; #pragma unroll
;                         for (int e = 0; e < 4; ++e) { const float a = fmaxf(v0[e], 0.f), b = fmaxf(v1[e], 0.f); v0[e] = a * a; v1[e] = b * b; } }
;                     u32x4 w; w.x = cvt_pk_bf16(v0[0], v0[1]); w.y = cvt_pk_bf16(v0[2], v0[3]); w.z = cvt_pk_bf16(v1[0], v1[1]); w.w = cvt_pk_bf16(v1[2], v1[3]);
;                     if (col0 + bj * CBS < ncols) *(u32x4*)(rowp + bj * CBS) = w; } }
.LBB0_1316:
	s_mov_b32 s101, 1
	v_lshl_add_u32 v148, s8, 8, v1
	v_ashrrev_i32_e32 v149, 31, v148
	v_max_f32_e32 v122, 0, v122
	v_max_f32_e32 v123, 0, v123
	v_max_f32_e32 v124, 0, v124
	v_lshl_or_b32 v146, s36, 8, v153
	v_lshlrev_b64 v[150:151], 13, v[148:149]
	v_mul_f32_e32 v157, v122, v122
	v_max_f32_e32 v122, v127, v127
	v_mul_f32_e32 v127, v123, v123
	v_max_f32_e32 v123, v128, v128
	v_mul_f32_e32 v128, v124, v124
	v_ashrrev_i32_e32 v147, 31, v146
	v_lshl_add_u64 v[150:151], s[52:53], 0, v[150:151]
	v_max_f32_e32 v122, 0, v122
	v_max_f32_e32 v123, 0, v123
	v_max_f32_e32 v124, 0, v129
	v_max_f32_e32 v125, 0, v125
	v_lshl_add_u64 v[150:151], v[146:147], 1, v[150:151]
	v_max_f32_e32 v126, 0, v126
	v_mul_f32_e32 v122, v122, v122
	v_mul_f32_e32 v123, v123, v123
	v_mul_f32_e32 v124, v124, v124
	v_mul_f32_e32 v125, v125, v125
	v_cmp_gt_i32_e32 vcc, 2.0, v146
	v_mul_f32_e32 v126, v126, v126
	v_cvt_pk_bf16_f32 v122, v126, v122
	v_cvt_pk_bf16_f32 v123, v123, v124
	v_cvt_pk_bf16_f32 v124, v157, v127
	v_cvt_pk_bf16_f32 v125, v128, v125
	s_and_saveexec_b64 s[8:9], vcc
	s_cbranch_execz .LBB0_1318
	global_store_dwordx4 v[150:151], v[122:125], off
